# KW assembly loop: diagonal-only (exec-masked) loads of the second table and ssm_d
# speedup vs baseline: 1.0474x; 1.0474x over previous
; __device__ __forceinline__ unsigned pk2(float lo, float hi) { const f32x2_h v = {lo, hi}; return __builtin_bit_cast(unsigned, __builtin_convertvector(v, bf16x2_h)); }
; __global__ void __launch_bounds__(512, 2) fwd_megakernel(Params p) {
;     ...
;         for (int i = gt; i < NG * 512 * 64; i += NGT) {
;             const int c8 = i & 1, j = (i >> 1) & 31, c = (i >> 6) & 15, ii = (i >> 10) & 31, g = i >> 15;
;             float v[8];
;             if (j < ii) { const float* s = KT + (((size_t)(g * 2 + 0) * TCH + (ii - j)) * 16 + c) * 16 + 8 * c8;
; #pragma unroll
;                 for (int e = 0; e < 8; ++e) v[e] = s[e]; }
;             else if (j > ii) { const float* s = KT + (((size_t)(g * 2 + 1) * TCH + (j - ii)) * 16 + c) * 16 + 8 * c8;
; #pragma unroll
;                 for (int e = 0; e < 8; ++e) v[e] = s[e]; }
;             else { const float* s0 = KT + (((size_t)(g * 2 + 0) * TCH) * 16 + c) * 16 + 8 * c8; const float* s1 = KT + (((size_t)(g * 2 + 1) * TCH) * 16 + c) * 16 + 8 * c8;
; #pragma unroll
;                 for (int e = 0; e < 8; ++e) v[e] = s0[e] + s1[e] + ((8 * c8 + e) == c ? ssm_d[g * 16 + c] : 0.f); }
;             u32x4 o; o.x = pk2(v[0], v[1]); o.y = pk2(v[2], v[3]); o.z = pk2(v[4], v[5]); o.w = pk2(v[6], v[7]);
;             *(u32x4*)(KW + ((size_t)g * 512 + ii * 16 + c) * 768 + j * 16 + 8 * c8) = o;
;         }
.LBB0_152:
	s_add_u32 s4, s76, 0x500000
	s_addc_u32 s5, s77, 0
	s_add_u32 s6, s76, 0x6100000
	s_addc_u32 s7, s77, 0
	s_mov_b64 s[8:9], s[66:67]
	v_and_b32_e32 v102, 1, v132
	v_bfe_u32 v103, v132, 1, 5
	v_bfe_u32 v104, v132, 6, 4
	v_bfe_u32 v105, v132, 10, 5
	v_lshrrev_b32_e32 v106, 15, v132
	v_sub_u32_e32 v107, v105, v103
	v_sub_u32_e32 v116, 0, v107
	v_max_i32_e32 v109, v107, v116
	v_lshrrev_b32_e32 v108, 31, v107
	v_cmp_eq_u32_e64 s[10:11], 0, v107
	v_lshlrev_b32_e32 v116, 16, v106
	v_lshl_add_u32 v116, v104, 6, v116
	v_lshl_add_u32 v116, v102, 5, v116
	v_add_u32_e32 v111, 0x8000, v116
	v_lshl_add_u32 v110, v108, 15, v116
	v_lshl_add_u32 v110, v109, 10, v110
	v_lshl_add_u32 v112, v106, 4, v104
	v_lshlrev_b32_e32 v112, 2, v112
	v_lshl_add_u32 v117, v105, 4, v104
	v_mul_u32_u24_e32 v117, 0x600, v117
	v_mul_u32_u24_e32 v116, 0xc0000, v106
	v_add_u32_e32 v113, v116, v117
	v_lshl_add_u32 v113, v103, 5, v113
	v_lshl_add_u32 v113, v102, 4, v113
	v_lshlrev_b32_e32 v116, 3, v102
	v_sub_u32_e32 v117, v104, v116
	v_cmp_eq_u32_e32 vcc, 0, v117
	s_nop 1
	v_cndmask_b32_e64 v102, 0, 1.0, vcc
	v_cmp_eq_u32_e32 vcc, 1, v117
	s_nop 1
	v_cndmask_b32_e64 v103, 0, 1.0, vcc
	v_cmp_eq_u32_e32 vcc, 2, v117
	s_nop 1
	v_cndmask_b32_e64 v105, 0, 1.0, vcc
	v_cmp_eq_u32_e32 vcc, 3, v117
	s_nop 1
	v_cndmask_b32_e64 v106, 0, 1.0, vcc
	v_cmp_eq_u32_e32 vcc, 4, v117
	s_nop 1
	v_cndmask_b32_e64 v107, 0, 1.0, vcc
	v_cmp_eq_u32_e32 vcc, 5, v117
	s_nop 1
	v_cndmask_b32_e64 v108, 0, 1.0, vcc
	v_cmp_eq_u32_e32 vcc, 6, v117
	s_nop 1
	v_cndmask_b32_e64 v109, 0, 1.0, vcc
	v_cmp_eq_u32_e32 vcc, 7, v117
	s_nop 1
	v_cndmask_b32_e64 v114, 0, 1.0, vcc
	global_load_dwordx4 v[0:3], v110, s[4:5]
	global_load_dwordx4 v[4:7], v110, s[4:5] offset:16
	s_mov_b64 s[12:13], exec
	s_mov_b64 exec, s[10:11]
	global_load_dwordx4 v[8:11], v111, s[4:5]
	global_load_dwordx4 v[12:15], v111, s[4:5] offset:16
	global_load_dword v96, v112, s[8:9]
	s_mov_b64 exec, s[12:13]
	s_add_u32 s4, s4, 0x40000
	s_addc_u32 s5, s5, 0
	s_add_u32 s8, s8, 0x100
	s_addc_u32 s9, s9, 0
	global_load_dwordx4 v[16:19], v110, s[4:5]
	global_load_dwordx4 v[20:23], v110, s[4:5] offset:16
	s_mov_b64 s[12:13], exec
	s_mov_b64 exec, s[10:11]
	global_load_dwordx4 v[24:27], v111, s[4:5]
	global_load_dwordx4 v[28:31], v111, s[4:5] offset:16
	global_load_dword v97, v112, s[8:9]
	s_mov_b64 exec, s[12:13]
	s_add_u32 s4, s4, 0x40000
	s_addc_u32 s5, s5, 0
	s_add_u32 s8, s8, 0x100
	s_addc_u32 s9, s9, 0
	global_load_dwordx4 v[32:35], v110, s[4:5]
	global_load_dwordx4 v[36:39], v110, s[4:5] offset:16
	s_mov_b64 s[12:13], exec
	s_mov_b64 exec, s[10:11]
	global_load_dwordx4 v[40:43], v111, s[4:5]
	global_load_dwordx4 v[44:47], v111, s[4:5] offset:16
	global_load_dword v98, v112, s[8:9]
	s_mov_b64 exec, s[12:13]
	s_add_u32 s4, s4, 0x40000
	s_addc_u32 s5, s5, 0
	s_add_u32 s8, s8, 0x100
	s_addc_u32 s9, s9, 0
	global_load_dwordx4 v[48:51], v110, s[4:5]
	global_load_dwordx4 v[52:55], v110, s[4:5] offset:16
	s_mov_b64 s[12:13], exec
	s_mov_b64 exec, s[10:11]
	global_load_dwordx4 v[56:59], v111, s[4:5]
	global_load_dwordx4 v[60:63], v111, s[4:5] offset:16
	global_load_dword v99, v112, s[8:9]
	s_mov_b64 exec, s[12:13]
	s_add_u32 s4, s4, 0x40000
	s_addc_u32 s5, s5, 0
	s_add_u32 s8, s8, 0x100
	s_addc_u32 s9, s9, 0
	global_load_dwordx4 v[64:67], v110, s[4:5]
	global_load_dwordx4 v[68:71], v110, s[4:5] offset:16
	s_mov_b64 s[12:13], exec
	s_mov_b64 exec, s[10:11]
	global_load_dwordx4 v[72:75], v111, s[4:5]
	global_load_dwordx4 v[76:79], v111, s[4:5] offset:16
	global_load_dword v100, v112, s[8:9]
	s_mov_b64 exec, s[12:13]
	s_add_u32 s4, s4, 0x40000
	s_addc_u32 s5, s5, 0
	s_add_u32 s8, s8, 0x100
	s_addc_u32 s9, s9, 0
	global_load_dwordx4 v[80:83], v110, s[4:5]
	global_load_dwordx4 v[84:87], v110, s[4:5] offset:16
	s_mov_b64 s[12:13], exec
	s_mov_b64 exec, s[10:11]
	global_load_dwordx4 v[88:91], v111, s[4:5]
	global_load_dwordx4 v[92:95], v111, s[4:5] offset:16
	global_load_dword v101, v112, s[8:9]
	s_mov_b64 exec, s[12:13]
	s_add_u32 s4, s4, 0x40000
	s_addc_u32 s5, s5, 0
	s_add_u32 s8, s8, 0x100
	s_addc_u32 s9, s9, 0
	s_waitcnt vmcnt(15)
	v_add_f32_e32 v8, v0, v8
	v_add_f32_e32 v9, v1, v9
	v_add_f32_e32 v10, v2, v10
	v_add_f32_e32 v11, v3, v11
	v_add_f32_e32 v12, v4, v12
	v_add_f32_e32 v13, v5, v13
	v_add_f32_e32 v14, v6, v14
	v_add_f32_e32 v15, v7, v15
	v_fma_f32 v8, v102, v96, v8
	v_fma_f32 v9, v103, v96, v9
	v_fma_f32 v10, v105, v96, v10
	v_fma_f32 v11, v106, v96, v11
	v_fma_f32 v12, v107, v96, v12
	v_fma_f32 v13, v108, v96, v13
	v_fma_f32 v14, v109, v96, v14
	v_fma_f32 v15, v114, v96, v15
	v_cndmask_b32_e64 v0, v0, v8, s[10:11]
	v_cndmask_b32_e64 v1, v1, v9, s[10:11]
	v_cndmask_b32_e64 v2, v2, v10, s[10:11]
	v_cndmask_b32_e64 v3, v3, v11, s[10:11]
	v_cndmask_b32_e64 v4, v4, v12, s[10:11]
	v_cndmask_b32_e64 v5, v5, v13, s[10:11]
	v_cndmask_b32_e64 v6, v6, v14, s[10:11]
	v_cndmask_b32_e64 v7, v7, v15, s[10:11]
	v_cvt_pk_bf16_f32 v0, v0, v1
	v_cvt_pk_bf16_f32 v1, v2, v3
	v_cvt_pk_bf16_f32 v2, v4, v5
	v_cvt_pk_bf16_f32 v3, v6, v7
	global_store_dwordx4 v113, v[0:3], s[6:7]
	s_add_u32 s6, s6, 0x300000
	s_addc_u32 s7, s7, 0
	v_add_f32_e32 v24, v16, v24
	v_add_f32_e32 v25, v17, v25
	v_add_f32_e32 v26, v18, v26
	v_add_f32_e32 v27, v19, v27
	v_add_f32_e32 v28, v20, v28
	v_add_f32_e32 v29, v21, v29
	v_add_f32_e32 v30, v22, v30
	v_add_f32_e32 v31, v23, v31
	v_fma_f32 v24, v102, v97, v24
	v_fma_f32 v25, v103, v97, v25
	v_fma_f32 v26, v105, v97, v26
	v_fma_f32 v27, v106, v97, v27
	v_fma_f32 v28, v107, v97, v28
	v_fma_f32 v29, v108, v97, v29
	v_fma_f32 v30, v109, v97, v30
	v_fma_f32 v31, v114, v97, v31
	v_cndmask_b32_e64 v16, v16, v24, s[10:11]
; __device__ __forceinline__ unsigned pk2(float lo, float hi) { const f32x2_h v = {lo, hi}; return __builtin_bit_cast(unsigned, __builtin_convertvector(v, bf16x2_h)); }
; __global__ void __launch_bounds__(512, 2) fwd_megakernel(Params p) {
;     ...
;         for (int i = gt; i < NG * 512 * 64; i += NGT) {
;             const int c8 = i & 1, j = (i >> 1) & 31, c = (i >> 6) & 15, ii = (i >> 10) & 31, g = i >> 15;
;             float v[8];
;             if (j < ii) { const float* s = KT + (((size_t)(g * 2 + 0) * TCH + (ii - j)) * 16 + c) * 16 + 8 * c8;
; #pragma unroll
;                 for (int e = 0; e < 8; ++e) v[e] = s[e]; }
;             else if (j > ii) { const float* s = KT + (((size_t)(g * 2 + 1) * TCH + (j - ii)) * 16 + c) * 16 + 8 * c8;
; #pragma unroll
;                 for (int e = 0; e < 8; ++e) v[e] = s[e]; }
;             else { const float* s0 = KT + (((size_t)(g * 2 + 0) * TCH) * 16 + c) * 16 + 8 * c8; const float* s1 = KT + (((size_t)(g * 2 + 1) * TCH) * 16 + c) * 16 + 8 * c8;
; #pragma unroll
;                 for (int e = 0; e < 8; ++e) v[e] = s0[e] + s1[e] + ((8 * c8 + e) == c ? ssm_d[g * 16 + c] : 0.f); }
;             u32x4 o; o.x = pk2(v[0], v[1]); o.y = pk2(v[2], v[3]); o.z = pk2(v[4], v[5]); o.w = pk2(v[6], v[7]);
;             *(u32x4*)(KW + ((size_t)g * 512 + ii * 16 + c) * 768 + j * 16 + 8 * c8) = o;
;         }
	v_cndmask_b32_e64 v17, v17, v25, s[10:11]
	v_cndmask_b32_e64 v18, v18, v26, s[10:11]
	v_cndmask_b32_e64 v19, v19, v27, s[10:11]
	v_cndmask_b32_e64 v20, v20, v28, s[10:11]
	v_cndmask_b32_e64 v21, v21, v29, s[10:11]
	v_cndmask_b32_e64 v22, v22, v30, s[10:11]
	v_cndmask_b32_e64 v23, v23, v31, s[10:11]
	v_cvt_pk_bf16_f32 v16, v16, v17
	v_cvt_pk_bf16_f32 v17, v18, v19
	v_cvt_pk_bf16_f32 v18, v20, v21
	v_cvt_pk_bf16_f32 v19, v22, v23
	global_store_dwordx4 v113, v[16:19], s[6:7]
	s_add_u32 s6, s6, 0x300000
	s_addc_u32 s7, s7, 0
	v_add_f32_e32 v40, v32, v40
	v_add_f32_e32 v41, v33, v41
	v_add_f32_e32 v42, v34, v42
	v_add_f32_e32 v43, v35, v43
	v_add_f32_e32 v44, v36, v44
	v_add_f32_e32 v45, v37, v45
	v_add_f32_e32 v46, v38, v46
	v_add_f32_e32 v47, v39, v47
	v_fma_f32 v40, v102, v98, v40
	v_fma_f32 v41, v103, v98, v41
	v_fma_f32 v42, v105, v98, v42
	v_fma_f32 v43, v106, v98, v43
	v_fma_f32 v44, v107, v98, v44
	v_fma_f32 v45, v108, v98, v45
	v_fma_f32 v46, v109, v98, v46
	v_fma_f32 v47, v114, v98, v47
	v_cndmask_b32_e64 v32, v32, v40, s[10:11]
	v_cndmask_b32_e64 v33, v33, v41, s[10:11]
	v_cndmask_b32_e64 v34, v34, v42, s[10:11]
	v_cndmask_b32_e64 v35, v35, v43, s[10:11]
	v_cndmask_b32_e64 v36, v36, v44, s[10:11]
	v_cndmask_b32_e64 v37, v37, v45, s[10:11]
	v_cndmask_b32_e64 v38, v38, v46, s[10:11]
	v_cndmask_b32_e64 v39, v39, v47, s[10:11]
	v_cvt_pk_bf16_f32 v32, v32, v33
	v_cvt_pk_bf16_f32 v33, v34, v35
	v_cvt_pk_bf16_f32 v34, v36, v37
	v_cvt_pk_bf16_f32 v35, v38, v39
	global_store_dwordx4 v113, v[32:35], s[6:7]
	s_add_u32 s6, s6, 0x300000
	s_addc_u32 s7, s7, 0
	global_load_dwordx4 v[0:3], v110, s[4:5]
	global_load_dwordx4 v[4:7], v110, s[4:5] offset:16
	s_mov_b64 s[12:13], exec
	s_mov_b64 exec, s[10:11]
	global_load_dwordx4 v[8:11], v111, s[4:5]
	global_load_dwordx4 v[12:15], v111, s[4:5] offset:16
	global_load_dword v96, v112, s[8:9]
	s_mov_b64 exec, s[12:13]
	s_add_u32 s4, s4, 0x40000
	s_addc_u32 s5, s5, 0
	s_add_u32 s8, s8, 0x100
	s_addc_u32 s9, s9, 0
	global_load_dwordx4 v[16:19], v110, s[4:5]
	global_load_dwordx4 v[20:23], v110, s[4:5] offset:16
	s_mov_b64 s[12:13], exec
	s_mov_b64 exec, s[10:11]
	global_load_dwordx4 v[24:27], v111, s[4:5]
	global_load_dwordx4 v[28:31], v111, s[4:5] offset:16
	global_load_dword v97, v112, s[8:9]
	s_mov_b64 exec, s[12:13]
	s_add_u32 s4, s4, 0x40000
	s_addc_u32 s5, s5, 0
	s_add_u32 s8, s8, 0x100
	s_addc_u32 s9, s9, 0
	global_load_dwordx4 v[32:35], v110, s[4:5]
	global_load_dwordx4 v[36:39], v110, s[4:5] offset:16
	s_mov_b64 s[12:13], exec
	s_mov_b64 exec, s[10:11]
	global_load_dwordx4 v[40:43], v111, s[4:5]
	global_load_dwordx4 v[44:47], v111, s[4:5] offset:16
	global_load_dword v98, v112, s[8:9]
	s_mov_b64 exec, s[12:13]
	s_add_u32 s4, s4, 0x40000
	s_addc_u32 s5, s5, 0
	s_add_u32 s8, s8, 0x100
	s_addc_u32 s9, s9, 0
	s_waitcnt vmcnt(18)
	v_add_f32_e32 v56, v48, v56
	v_add_f32_e32 v57, v49, v57
	v_add_f32_e32 v58, v50, v58
	v_add_f32_e32 v59, v51, v59
	v_add_f32_e32 v60, v52, v60
	v_add_f32_e32 v61, v53, v61
	v_add_f32_e32 v62, v54, v62
	v_add_f32_e32 v63, v55, v63
	v_fma_f32 v56, v102, v99, v56
	v_fma_f32 v57, v103, v99, v57
	v_fma_f32 v58, v105, v99, v58
	v_fma_f32 v59, v106, v99, v59
	v_fma_f32 v60, v107, v99, v60
	v_fma_f32 v61, v108, v99, v61
	v_fma_f32 v62, v109, v99, v62
	v_fma_f32 v63, v114, v99, v63
	v_cndmask_b32_e64 v48, v48, v56, s[10:11]
	v_cndmask_b32_e64 v49, v49, v57, s[10:11]
	v_cndmask_b32_e64 v50, v50, v58, s[10:11]
	v_cndmask_b32_e64 v51, v51, v59, s[10:11]
	v_cndmask_b32_e64 v52, v52, v60, s[10:11]
	v_cndmask_b32_e64 v53, v53, v61, s[10:11]
	v_cndmask_b32_e64 v54, v54, v62, s[10:11]
	v_cndmask_b32_e64 v55, v55, v63, s[10:11]
	v_cvt_pk_bf16_f32 v48, v48, v49
	v_cvt_pk_bf16_f32 v49, v50, v51
	v_cvt_pk_bf16_f32 v50, v52, v53
	v_cvt_pk_bf16_f32 v51, v54, v55
	global_store_dwordx4 v113, v[48:51], s[6:7]
	s_add_u32 s6, s6, 0x300000
	s_addc_u32 s7, s7, 0
	v_add_f32_e32 v72, v64, v72
	v_add_f32_e32 v73, v65, v73
	v_add_f32_e32 v74, v66, v74
	v_add_f32_e32 v75, v67, v75
	v_add_f32_e32 v76, v68, v76
	v_add_f32_e32 v77, v69, v77
	v_add_f32_e32 v78, v70, v78
	v_add_f32_e32 v79, v71, v79
	v_fma_f32 v72, v102, v100, v72
	v_fma_f32 v73, v103, v100, v73
	v_fma_f32 v74, v105, v100, v74
	v_fma_f32 v75, v106, v100, v75
	v_fma_f32 v76, v107, v100, v76
	v_fma_f32 v77, v108, v100, v77
	v_fma_f32 v78, v109, v100, v78
	v_fma_f32 v79, v114, v100, v79
	v_cndmask_b32_e64 v64, v64, v72, s[10:11]
	v_cndmask_b32_e64 v65, v65, v73, s[10:11]
	v_cndmask_b32_e64 v66, v66, v74, s[10:11]
	v_cndmask_b32_e64 v67, v67, v75, s[10:11]
	v_cndmask_b32_e64 v68, v68, v76, s[10:11]
	v_cndmask_b32_e64 v69, v69, v77, s[10:11]
	v_cndmask_b32_e64 v70, v70, v78, s[10:11]
	v_cndmask_b32_e64 v71, v71, v79, s[10:11]
	v_cvt_pk_bf16_f32 v64, v64, v65
	v_cvt_pk_bf16_f32 v65, v66, v67
	v_cvt_pk_bf16_f32 v66, v68, v69
	v_cvt_pk_bf16_f32 v67, v70, v71
	global_store_dwordx4 v113, v[64:67], s[6:7]
	s_add_u32 s6, s6, 0x300000
	s_addc_u32 s7, s7, 0
	v_add_f32_e32 v88, v80, v88
	v_add_f32_e32 v89, v81, v89
	v_add_f32_e32 v90, v82, v90
	v_add_f32_e32 v91, v83, v91
	v_add_f32_e32 v92, v84, v92
	v_add_f32_e32 v93, v85, v93
	v_add_f32_e32 v94, v86, v94
	v_add_f32_e32 v95, v87, v95
	v_fma_f32 v88, v102, v101, v88
	v_fma_f32 v89, v103, v101, v89
	v_fma_f32 v90, v105, v101, v90
	v_fma_f32 v91, v106, v101, v91
	v_fma_f32 v92, v107, v101, v92
	v_fma_f32 v93, v108, v101, v93
	v_fma_f32 v94, v109, v101, v94
	v_fma_f32 v95, v114, v101, v95
	v_cndmask_b32_e64 v80, v80, v88, s[10:11]
	v_cndmask_b32_e64 v81, v81, v89, s[10:11]
	v_cndmask_b32_e64 v82, v82, v90, s[10:11]
	v_cndmask_b32_e64 v83, v83, v91, s[10:11]
	v_cndmask_b32_e64 v84, v84, v92, s[10:11]
; __device__ __forceinline__ unsigned pk2(float lo, float hi) { const f32x2_h v = {lo, hi}; return __builtin_bit_cast(unsigned, __builtin_convertvector(v, bf16x2_h)); }
; __global__ void __launch_bounds__(512, 2) fwd_megakernel(Params p) {
;     ...
;         for (int i = gt; i < NG * 512 * 64; i += NGT) {
;             const int c8 = i & 1, j = (i >> 1) & 31, c = (i >> 6) & 15, ii = (i >> 10) & 31, g = i >> 15;
;             float v[8];
;             if (j < ii) { const float* s = KT + (((size_t)(g * 2 + 0) * TCH + (ii - j)) * 16 + c) * 16 + 8 * c8;
; #pragma unroll
;                 for (int e = 0; e < 8; ++e) v[e] = s[e]; }
;             else if (j > ii) { const float* s = KT + (((size_t)(g * 2 + 1) * TCH + (j - ii)) * 16 + c) * 16 + 8 * c8;
; #pragma unroll
;                 for (int e = 0; e < 8; ++e) v[e] = s[e]; }
;             else { const float* s0 = KT + (((size_t)(g * 2 + 0) * TCH) * 16 + c) * 16 + 8 * c8; const float* s1 = KT + (((size_t)(g * 2 + 1) * TCH) * 16 + c) * 16 + 8 * c8;
; #pragma unroll
;                 for (int e = 0; e < 8; ++e) v[e] = s0[e] + s1[e] + ((8 * c8 + e) == c ? ssm_d[g * 16 + c] : 0.f); }
;             u32x4 o; o.x = pk2(v[0], v[1]); o.y = pk2(v[2], v[3]); o.z = pk2(v[4], v[5]); o.w = pk2(v[6], v[7]);
;             *(u32x4*)(KW + ((size_t)g * 512 + ii * 16 + c) * 768 + j * 16 + 8 * c8) = o;
;         }
	v_cndmask_b32_e64 v85, v85, v93, s[10:11]
	v_cndmask_b32_e64 v86, v86, v94, s[10:11]
	v_cndmask_b32_e64 v87, v87, v95, s[10:11]
	v_cvt_pk_bf16_f32 v80, v80, v81
	v_cvt_pk_bf16_f32 v81, v82, v83
	v_cvt_pk_bf16_f32 v82, v84, v85
	v_cvt_pk_bf16_f32 v83, v86, v87
	global_store_dwordx4 v113, v[80:83], s[6:7]
	s_add_u32 s6, s6, 0x300000
	s_addc_u32 s7, s7, 0
	global_load_dwordx4 v[48:51], v110, s[4:5]
	global_load_dwordx4 v[52:55], v110, s[4:5] offset:16
	s_mov_b64 s[12:13], exec
	s_mov_b64 exec, s[10:11]
	global_load_dwordx4 v[56:59], v111, s[4:5]
	global_load_dwordx4 v[60:63], v111, s[4:5] offset:16
	global_load_dword v99, v112, s[8:9]
	s_mov_b64 exec, s[12:13]
	s_add_u32 s4, s4, 0x40000
	s_addc_u32 s5, s5, 0
	s_add_u32 s8, s8, 0x100
	s_addc_u32 s9, s9, 0
	global_load_dwordx4 v[64:67], v110, s[4:5]
	global_load_dwordx4 v[68:71], v110, s[4:5] offset:16
	s_mov_b64 s[12:13], exec
	s_mov_b64 exec, s[10:11]
	global_load_dwordx4 v[72:75], v111, s[4:5]
	global_load_dwordx4 v[76:79], v111, s[4:5] offset:16
	global_load_dword v100, v112, s[8:9]
	s_mov_b64 exec, s[12:13]
	s_add_u32 s4, s4, 0x40000
	s_addc_u32 s5, s5, 0
	s_add_u32 s8, s8, 0x100
	s_addc_u32 s9, s9, 0
	global_load_dwordx4 v[80:83], v110, s[4:5]
	global_load_dwordx4 v[84:87], v110, s[4:5] offset:16
	s_mov_b64 s[12:13], exec
	s_mov_b64 exec, s[10:11]
	global_load_dwordx4 v[88:91], v111, s[4:5]
	global_load_dwordx4 v[92:95], v111, s[4:5] offset:16
	global_load_dword v101, v112, s[8:9]
	s_mov_b64 exec, s[12:13]
	s_add_u32 s4, s4, 0x40000
	s_addc_u32 s5, s5, 0
	s_add_u32 s8, s8, 0x100
	s_addc_u32 s9, s9, 0
	s_waitcnt vmcnt(18)
	v_add_f32_e32 v8, v0, v8
	v_add_f32_e32 v9, v1, v9
	v_add_f32_e32 v10, v2, v10
	v_add_f32_e32 v11, v3, v11
	v_add_f32_e32 v12, v4, v12
	v_add_f32_e32 v13, v5, v13
	v_add_f32_e32 v14, v6, v14
	v_add_f32_e32 v15, v7, v15
	v_fma_f32 v8, v102, v96, v8
	v_fma_f32 v9, v103, v96, v9
	v_fma_f32 v10, v105, v96, v10
	v_fma_f32 v11, v106, v96, v11
	v_fma_f32 v12, v107, v96, v12
	v_fma_f32 v13, v108, v96, v13
	v_fma_f32 v14, v109, v96, v14
	v_fma_f32 v15, v114, v96, v15
	v_cndmask_b32_e64 v0, v0, v8, s[10:11]
	v_cndmask_b32_e64 v1, v1, v9, s[10:11]
	v_cndmask_b32_e64 v2, v2, v10, s[10:11]
	v_cndmask_b32_e64 v3, v3, v11, s[10:11]
	v_cndmask_b32_e64 v4, v4, v12, s[10:11]
	v_cndmask_b32_e64 v5, v5, v13, s[10:11]
	v_cndmask_b32_e64 v6, v6, v14, s[10:11]
	v_cndmask_b32_e64 v7, v7, v15, s[10:11]
	v_cvt_pk_bf16_f32 v0, v0, v1
	v_cvt_pk_bf16_f32 v1, v2, v3
	v_cvt_pk_bf16_f32 v2, v4, v5
	v_cvt_pk_bf16_f32 v3, v6, v7
	global_store_dwordx4 v113, v[0:3], s[6:7]
	s_add_u32 s6, s6, 0x300000
	s_addc_u32 s7, s7, 0
	v_add_f32_e32 v24, v16, v24
	v_add_f32_e32 v25, v17, v25
	v_add_f32_e32 v26, v18, v26
	v_add_f32_e32 v27, v19, v27
	v_add_f32_e32 v28, v20, v28
	v_add_f32_e32 v29, v21, v29
	v_add_f32_e32 v30, v22, v30
	v_add_f32_e32 v31, v23, v31
	v_fma_f32 v24, v102, v97, v24
	v_fma_f32 v25, v103, v97, v25
	v_fma_f32 v26, v105, v97, v26
	v_fma_f32 v27, v106, v97, v27
	v_fma_f32 v28, v107, v97, v28
	v_fma_f32 v29, v108, v97, v29
	v_fma_f32 v30, v109, v97, v30
	v_fma_f32 v31, v114, v97, v31
	v_cndmask_b32_e64 v16, v16, v24, s[10:11]
	v_cndmask_b32_e64 v17, v17, v25, s[10:11]
	v_cndmask_b32_e64 v18, v18, v26, s[10:11]
	v_cndmask_b32_e64 v19, v19, v27, s[10:11]
	v_cndmask_b32_e64 v20, v20, v28, s[10:11]
	v_cndmask_b32_e64 v21, v21, v29, s[10:11]
	v_cndmask_b32_e64 v22, v22, v30, s[10:11]
	v_cndmask_b32_e64 v23, v23, v31, s[10:11]
	v_cvt_pk_bf16_f32 v16, v16, v17
	v_cvt_pk_bf16_f32 v17, v18, v19
	v_cvt_pk_bf16_f32 v18, v20, v21
	v_cvt_pk_bf16_f32 v19, v22, v23
	global_store_dwordx4 v113, v[16:19], s[6:7]
	s_add_u32 s6, s6, 0x300000
	s_addc_u32 s7, s7, 0
	v_add_f32_e32 v40, v32, v40
	v_add_f32_e32 v41, v33, v41
	v_add_f32_e32 v42, v34, v42
	v_add_f32_e32 v43, v35, v43
	v_add_f32_e32 v44, v36, v44
	v_add_f32_e32 v45, v37, v45
	v_add_f32_e32 v46, v38, v46
	v_add_f32_e32 v47, v39, v47
	v_fma_f32 v40, v102, v98, v40
	v_fma_f32 v41, v103, v98, v41
	v_fma_f32 v42, v105, v98, v42
	v_fma_f32 v43, v106, v98, v43
	v_fma_f32 v44, v107, v98, v44
	v_fma_f32 v45, v108, v98, v45
	v_fma_f32 v46, v109, v98, v46
	v_fma_f32 v47, v114, v98, v47
	v_cndmask_b32_e64 v32, v32, v40, s[10:11]
	v_cndmask_b32_e64 v33, v33, v41, s[10:11]
	v_cndmask_b32_e64 v34, v34, v42, s[10:11]
	v_cndmask_b32_e64 v35, v35, v43, s[10:11]
	v_cndmask_b32_e64 v36, v36, v44, s[10:11]
	v_cndmask_b32_e64 v37, v37, v45, s[10:11]
	v_cndmask_b32_e64 v38, v38, v46, s[10:11]
	v_cndmask_b32_e64 v39, v39, v47, s[10:11]
	v_cvt_pk_bf16_f32 v32, v32, v33
	v_cvt_pk_bf16_f32 v33, v34, v35
	v_cvt_pk_bf16_f32 v34, v36, v37
	v_cvt_pk_bf16_f32 v35, v38, v39
	global_store_dwordx4 v113, v[32:35], s[6:7]
	s_add_u32 s6, s6, 0x300000
	s_addc_u32 s7, s7, 0
	global_load_dwordx4 v[0:3], v110, s[4:5]
	global_load_dwordx4 v[4:7], v110, s[4:5] offset:16
	s_mov_b64 s[12:13], exec
	s_mov_b64 exec, s[10:11]
	global_load_dwordx4 v[8:11], v111, s[4:5]
	global_load_dwordx4 v[12:15], v111, s[4:5] offset:16
	global_load_dword v96, v112, s[8:9]
	s_mov_b64 exec, s[12:13]
	s_add_u32 s4, s4, 0x40000
	s_addc_u32 s5, s5, 0
	s_add_u32 s8, s8, 0x100
	s_addc_u32 s9, s9, 0
	global_load_dwordx4 v[16:19], v110, s[4:5]
	global_load_dwordx4 v[20:23], v110, s[4:5] offset:16
	s_mov_b64 s[12:13], exec
	s_mov_b64 exec, s[10:11]
	global_load_dwordx4 v[24:27], v111, s[4:5]
	global_load_dwordx4 v[28:31], v111, s[4:5] offset:16
	global_load_dword v97, v112, s[8:9]
	s_mov_b64 exec, s[12:13]
	s_add_u32 s4, s4, 0x40000
	s_addc_u32 s5, s5, 0
	s_add_u32 s8, s8, 0x100
	s_addc_u32 s9, s9, 0
	global_load_dwordx4 v[32:35], v110, s[4:5]
	global_load_dwordx4 v[36:39], v110, s[4:5] offset:16
	s_mov_b64 s[12:13], exec
	s_mov_b64 exec, s[10:11]
	global_load_dwordx4 v[40:43], v111, s[4:5]
	global_load_dwordx4 v[44:47], v111, s[4:5] offset:16
	global_load_dword v98, v112, s[8:9]
	s_mov_b64 exec, s[12:13]
	s_add_u32 s4, s4, 0x40000
	s_addc_u32 s5, s5, 0
	s_add_u32 s8, s8, 0x100
	s_addc_u32 s9, s9, 0
	s_waitcnt vmcnt(18)
; __device__ __forceinline__ unsigned pk2(float lo, float hi) { const f32x2_h v = {lo, hi}; return __builtin_bit_cast(unsigned, __builtin_convertvector(v, bf16x2_h)); }
; __global__ void __launch_bounds__(512, 2) fwd_megakernel(Params p) {
;     ...
;         for (int i = gt; i < NG * 512 * 64; i += NGT) {
;             const int c8 = i & 1, j = (i >> 1) & 31, c = (i >> 6) & 15, ii = (i >> 10) & 31, g = i >> 15;
;             float v[8];
;             if (j < ii) { const float* s = KT + (((size_t)(g * 2 + 0) * TCH + (ii - j)) * 16 + c) * 16 + 8 * c8;
; #pragma unroll
;                 for (int e = 0; e < 8; ++e) v[e] = s[e]; }
;             else if (j > ii) { const float* s = KT + (((size_t)(g * 2 + 1) * TCH + (j - ii)) * 16 + c) * 16 + 8 * c8;
; #pragma unroll
;                 for (int e = 0; e < 8; ++e) v[e] = s[e]; }
;             else { const float* s0 = KT + (((size_t)(g * 2 + 0) * TCH) * 16 + c) * 16 + 8 * c8; const float* s1 = KT + (((size_t)(g * 2 + 1) * TCH) * 16 + c) * 16 + 8 * c8;
; #pragma unroll
;                 for (int e = 0; e < 8; ++e) v[e] = s0[e] + s1[e] + ((8 * c8 + e) == c ? ssm_d[g * 16 + c] : 0.f); }
;             u32x4 o; o.x = pk2(v[0], v[1]); o.y = pk2(v[2], v[3]); o.z = pk2(v[4], v[5]); o.w = pk2(v[6], v[7]);
;             *(u32x4*)(KW + ((size_t)g * 512 + ii * 16 + c) * 768 + j * 16 + 8 * c8) = o;
;         }
	v_add_f32_e32 v56, v48, v56
	v_add_f32_e32 v57, v49, v57
	v_add_f32_e32 v58, v50, v58
	v_add_f32_e32 v59, v51, v59
	v_add_f32_e32 v60, v52, v60
	v_add_f32_e32 v61, v53, v61
	v_add_f32_e32 v62, v54, v62
	v_add_f32_e32 v63, v55, v63
	v_fma_f32 v56, v102, v99, v56
	v_fma_f32 v57, v103, v99, v57
	v_fma_f32 v58, v105, v99, v58
	v_fma_f32 v59, v106, v99, v59
	v_fma_f32 v60, v107, v99, v60
	v_fma_f32 v61, v108, v99, v61
	v_fma_f32 v62, v109, v99, v62
	v_fma_f32 v63, v114, v99, v63
	v_cndmask_b32_e64 v48, v48, v56, s[10:11]
	v_cndmask_b32_e64 v49, v49, v57, s[10:11]
	v_cndmask_b32_e64 v50, v50, v58, s[10:11]
	v_cndmask_b32_e64 v51, v51, v59, s[10:11]
	v_cndmask_b32_e64 v52, v52, v60, s[10:11]
	v_cndmask_b32_e64 v53, v53, v61, s[10:11]
	v_cndmask_b32_e64 v54, v54, v62, s[10:11]
	v_cndmask_b32_e64 v55, v55, v63, s[10:11]
	v_cvt_pk_bf16_f32 v48, v48, v49
	v_cvt_pk_bf16_f32 v49, v50, v51
	v_cvt_pk_bf16_f32 v50, v52, v53
	v_cvt_pk_bf16_f32 v51, v54, v55
	global_store_dwordx4 v113, v[48:51], s[6:7]
	s_add_u32 s6, s6, 0x300000
	s_addc_u32 s7, s7, 0
	v_add_f32_e32 v72, v64, v72
	v_add_f32_e32 v73, v65, v73
	v_add_f32_e32 v74, v66, v74
	v_add_f32_e32 v75, v67, v75
	v_add_f32_e32 v76, v68, v76
	v_add_f32_e32 v77, v69, v77
	v_add_f32_e32 v78, v70, v78
	v_add_f32_e32 v79, v71, v79
	v_fma_f32 v72, v102, v100, v72
	v_fma_f32 v73, v103, v100, v73
	v_fma_f32 v74, v105, v100, v74
	v_fma_f32 v75, v106, v100, v75
	v_fma_f32 v76, v107, v100, v76
	v_fma_f32 v77, v108, v100, v77
	v_fma_f32 v78, v109, v100, v78
	v_fma_f32 v79, v114, v100, v79
	v_cndmask_b32_e64 v64, v64, v72, s[10:11]
	v_cndmask_b32_e64 v65, v65, v73, s[10:11]
	v_cndmask_b32_e64 v66, v66, v74, s[10:11]
	v_cndmask_b32_e64 v67, v67, v75, s[10:11]
	v_cndmask_b32_e64 v68, v68, v76, s[10:11]
	v_cndmask_b32_e64 v69, v69, v77, s[10:11]
	v_cndmask_b32_e64 v70, v70, v78, s[10:11]
	v_cndmask_b32_e64 v71, v71, v79, s[10:11]
	v_cvt_pk_bf16_f32 v64, v64, v65
	v_cvt_pk_bf16_f32 v65, v66, v67
	v_cvt_pk_bf16_f32 v66, v68, v69
	v_cvt_pk_bf16_f32 v67, v70, v71
	global_store_dwordx4 v113, v[64:67], s[6:7]
	s_add_u32 s6, s6, 0x300000
	s_addc_u32 s7, s7, 0
	v_add_f32_e32 v88, v80, v88
	v_add_f32_e32 v89, v81, v89
	v_add_f32_e32 v90, v82, v90
	v_add_f32_e32 v91, v83, v91
	v_add_f32_e32 v92, v84, v92
	v_add_f32_e32 v93, v85, v93
	v_add_f32_e32 v94, v86, v94
	v_add_f32_e32 v95, v87, v95
	v_fma_f32 v88, v102, v101, v88
	v_fma_f32 v89, v103, v101, v89
	v_fma_f32 v90, v105, v101, v90
	v_fma_f32 v91, v106, v101, v91
	v_fma_f32 v92, v107, v101, v92
	v_fma_f32 v93, v108, v101, v93
	v_fma_f32 v94, v109, v101, v94
	v_fma_f32 v95, v114, v101, v95
	v_cndmask_b32_e64 v80, v80, v88, s[10:11]
	v_cndmask_b32_e64 v81, v81, v89, s[10:11]
	v_cndmask_b32_e64 v82, v82, v90, s[10:11]
	v_cndmask_b32_e64 v83, v83, v91, s[10:11]
	v_cndmask_b32_e64 v84, v84, v92, s[10:11]
	v_cndmask_b32_e64 v85, v85, v93, s[10:11]
	v_cndmask_b32_e64 v86, v86, v94, s[10:11]
	v_cndmask_b32_e64 v87, v87, v95, s[10:11]
	v_cvt_pk_bf16_f32 v80, v80, v81
	v_cvt_pk_bf16_f32 v81, v82, v83
	v_cvt_pk_bf16_f32 v82, v84, v85
	v_cvt_pk_bf16_f32 v83, v86, v87
	global_store_dwordx4 v113, v[80:83], s[6:7]
	s_add_u32 s6, s6, 0x300000
	s_addc_u32 s7, s7, 0
	global_load_dwordx4 v[48:51], v110, s[4:5]
	global_load_dwordx4 v[52:55], v110, s[4:5] offset:16
	s_mov_b64 s[12:13], exec
	s_mov_b64 exec, s[10:11]
	global_load_dwordx4 v[56:59], v111, s[4:5]
	global_load_dwordx4 v[60:63], v111, s[4:5] offset:16
	global_load_dword v99, v112, s[8:9]
	s_mov_b64 exec, s[12:13]
	s_add_u32 s4, s4, 0x40000
	s_addc_u32 s5, s5, 0
	s_add_u32 s8, s8, 0x100
	s_addc_u32 s9, s9, 0
	s_waitcnt vmcnt(8)
; __device__ __forceinline__ unsigned pk2(float lo, float hi) { const f32x2_h v = {lo, hi}; return __builtin_bit_cast(unsigned, __builtin_convertvector(v, bf16x2_h)); }
; __global__ void __launch_bounds__(512, 2) fwd_megakernel(Params p) {
;     ...
;         for (int i = gt; i < NG * 512 * 64; i += NGT) {
;             const int c8 = i & 1, j = (i >> 1) & 31, c = (i >> 6) & 15, ii = (i >> 10) & 31, g = i >> 15;
;             float v[8];
;             if (j < ii) { const float* s = KT + (((size_t)(g * 2 + 0) * TCH + (ii - j)) * 16 + c) * 16 + 8 * c8;
; #pragma unroll
;                 for (int e = 0; e < 8; ++e) v[e] = s[e]; }
;             else if (j > ii) { const float* s = KT + (((size_t)(g * 2 + 1) * TCH + (j - ii)) * 16 + c) * 16 + 8 * c8;
; #pragma unroll
;                 for (int e = 0; e < 8; ++e) v[e] = s[e]; }
;             else { const float* s0 = KT + (((size_t)(g * 2 + 0) * TCH) * 16 + c) * 16 + 8 * c8; const float* s1 = KT + (((size_t)(g * 2 + 1) * TCH) * 16 + c) * 16 + 8 * c8;
; #pragma unroll
;                 for (int e = 0; e < 8; ++e) v[e] = s0[e] + s1[e] + ((8 * c8 + e) == c ? ssm_d[g * 16 + c] : 0.f); }
;             u32x4 o; o.x = pk2(v[0], v[1]); o.y = pk2(v[2], v[3]); o.z = pk2(v[4], v[5]); o.w = pk2(v[6], v[7]);
;             *(u32x4*)(KW + ((size_t)g * 512 + ii * 16 + c) * 768 + j * 16 + 8 * c8) = o;
;         }
	v_add_f32_e32 v8, v0, v8
	v_add_f32_e32 v9, v1, v9
	v_add_f32_e32 v10, v2, v10
	v_add_f32_e32 v11, v3, v11
	v_add_f32_e32 v12, v4, v12
	v_add_f32_e32 v13, v5, v13
	v_add_f32_e32 v14, v6, v14
	v_add_f32_e32 v15, v7, v15
	v_fma_f32 v8, v102, v96, v8
	v_fma_f32 v9, v103, v96, v9
	v_fma_f32 v10, v105, v96, v10
	v_fma_f32 v11, v106, v96, v11
	v_fma_f32 v12, v107, v96, v12
	v_fma_f32 v13, v108, v96, v13
	v_fma_f32 v14, v109, v96, v14
	v_fma_f32 v15, v114, v96, v15
	v_cndmask_b32_e64 v0, v0, v8, s[10:11]
	v_cndmask_b32_e64 v1, v1, v9, s[10:11]
	v_cndmask_b32_e64 v2, v2, v10, s[10:11]
	v_cndmask_b32_e64 v3, v3, v11, s[10:11]
	v_cndmask_b32_e64 v4, v4, v12, s[10:11]
	v_cndmask_b32_e64 v5, v5, v13, s[10:11]
	v_cndmask_b32_e64 v6, v6, v14, s[10:11]
	v_cndmask_b32_e64 v7, v7, v15, s[10:11]
	v_cvt_pk_bf16_f32 v0, v0, v1
	v_cvt_pk_bf16_f32 v1, v2, v3
	v_cvt_pk_bf16_f32 v2, v4, v5
	v_cvt_pk_bf16_f32 v3, v6, v7
	global_store_dwordx4 v113, v[0:3], s[6:7]
	s_add_u32 s6, s6, 0x300000
	s_addc_u32 s7, s7, 0
	v_add_f32_e32 v24, v16, v24
	v_add_f32_e32 v25, v17, v25
	v_add_f32_e32 v26, v18, v26
	v_add_f32_e32 v27, v19, v27
	v_add_f32_e32 v28, v20, v28
	v_add_f32_e32 v29, v21, v29
	v_add_f32_e32 v30, v22, v30
	v_add_f32_e32 v31, v23, v31
	v_fma_f32 v24, v102, v97, v24
	v_fma_f32 v25, v103, v97, v25
	v_fma_f32 v26, v105, v97, v26
	v_fma_f32 v27, v106, v97, v27
	v_fma_f32 v28, v107, v97, v28
	v_fma_f32 v29, v108, v97, v29
	v_fma_f32 v30, v109, v97, v30
	v_fma_f32 v31, v114, v97, v31
	v_cndmask_b32_e64 v16, v16, v24, s[10:11]
	v_cndmask_b32_e64 v17, v17, v25, s[10:11]
	v_cndmask_b32_e64 v18, v18, v26, s[10:11]
	v_cndmask_b32_e64 v19, v19, v27, s[10:11]
	v_cndmask_b32_e64 v20, v20, v28, s[10:11]
	v_cndmask_b32_e64 v21, v21, v29, s[10:11]
	v_cndmask_b32_e64 v22, v22, v30, s[10:11]
	v_cndmask_b32_e64 v23, v23, v31, s[10:11]
	v_cvt_pk_bf16_f32 v16, v16, v17
	v_cvt_pk_bf16_f32 v17, v18, v19
	v_cvt_pk_bf16_f32 v18, v20, v21
	v_cvt_pk_bf16_f32 v19, v22, v23
	global_store_dwordx4 v113, v[16:19], s[6:7]
	s_add_u32 s6, s6, 0x300000
	s_addc_u32 s7, s7, 0
	v_add_f32_e32 v40, v32, v40
	v_add_f32_e32 v41, v33, v41
	v_add_f32_e32 v42, v34, v42
	v_add_f32_e32 v43, v35, v43
	v_add_f32_e32 v44, v36, v44
	v_add_f32_e32 v45, v37, v45
	v_add_f32_e32 v46, v38, v46
	v_add_f32_e32 v47, v39, v47
	v_fma_f32 v40, v102, v98, v40
	v_fma_f32 v41, v103, v98, v41
	v_fma_f32 v42, v105, v98, v42
	v_fma_f32 v43, v106, v98, v43
	v_fma_f32 v44, v107, v98, v44
	v_fma_f32 v45, v108, v98, v45
	v_fma_f32 v46, v109, v98, v46
	v_fma_f32 v47, v114, v98, v47
	v_cndmask_b32_e64 v32, v32, v40, s[10:11]
	v_cndmask_b32_e64 v33, v33, v41, s[10:11]
	v_cndmask_b32_e64 v34, v34, v42, s[10:11]
	v_cndmask_b32_e64 v35, v35, v43, s[10:11]
	v_cndmask_b32_e64 v36, v36, v44, s[10:11]
	v_cndmask_b32_e64 v37, v37, v45, s[10:11]
	v_cndmask_b32_e64 v38, v38, v46, s[10:11]
	v_cndmask_b32_e64 v39, v39, v47, s[10:11]
	v_cvt_pk_bf16_f32 v32, v32, v33
	v_cvt_pk_bf16_f32 v33, v34, v35
	v_cvt_pk_bf16_f32 v34, v36, v37
	v_cvt_pk_bf16_f32 v35, v38, v39
	global_store_dwordx4 v113, v[32:35], s[6:7]
	s_add_u32 s6, s6, 0x300000
	s_addc_u32 s7, s7, 0
	s_waitcnt vmcnt(3)
	v_add_f32_e32 v56, v48, v56
	v_add_f32_e32 v57, v49, v57
	v_add_f32_e32 v58, v50, v58
	v_add_f32_e32 v59, v51, v59
	v_add_f32_e32 v60, v52, v60
	v_add_f32_e32 v61, v53, v61
	v_add_f32_e32 v62, v54, v62
	v_add_f32_e32 v63, v55, v63
	v_fma_f32 v56, v102, v99, v56
	v_fma_f32 v57, v103, v99, v57
	v_fma_f32 v58, v105, v99, v58
	v_fma_f32 v59, v106, v99, v59
	v_fma_f32 v60, v107, v99, v60
	v_fma_f32 v61, v108, v99, v61
	v_fma_f32 v62, v109, v99, v62
	v_fma_f32 v63, v114, v99, v63
	v_cndmask_b32_e64 v48, v48, v56, s[10:11]
	v_cndmask_b32_e64 v49, v49, v57, s[10:11]
	v_cndmask_b32_e64 v50, v50, v58, s[10:11]
	v_cndmask_b32_e64 v51, v51, v59, s[10:11]
	v_cndmask_b32_e64 v52, v52, v60, s[10:11]
	v_cndmask_b32_e64 v53, v53, v61, s[10:11]
	v_cndmask_b32_e64 v54, v54, v62, s[10:11]
	v_cndmask_b32_e64 v55, v55, v63, s[10:11]
	v_cvt_pk_bf16_f32 v48, v48, v49
	v_cvt_pk_bf16_f32 v49, v50, v51
	v_cvt_pk_bf16_f32 v50, v52, v53
	v_cvt_pk_bf16_f32 v51, v54, v55
	global_store_dwordx4 v113, v[48:51], s[6:7]
	s_add_u32 s6, s6, 0x300000
	s_addc_u32 s7, s7, 0
